# grid barrier leader path: dropped the waits that only covered the acks of its own no-return release adds
# speedup vs baseline: 1.0104x; 1.0004x over previous
; __device__ __forceinline__ unsigned xb_ld(unsigned* p)              { return __hip_atomic_load(p, __ATOMIC_RELAXED, __HIP_MEMORY_SCOPE_AGENT); }
; __device__ __forceinline__ unsigned xb_add(unsigned* p, unsigned v) { return __hip_atomic_fetch_add(p, v, __ATOMIC_RELAXED, __HIP_MEMORY_SCOPE_AGENT); }
; #define XB_SPIN(cond, bar) do { unsigned _sp = 0; while (cond) { __builtin_amdgcn_s_sleep(1); \
;     if ((++_sp & 255u) == 0u) { if (xb_ld(&(bar)[XB_TMO])) break; if (_sp > XB_SPIN_CAP) { atomicAdd(&(bar)[XB_TMO], 1u); break; } } } } while (0)
; __device__ __forceinline__ void xcd_barrier(const XcdBarrier& b, int wave_id) {
;     ...
;             const unsigned og = xb_add(&bar[XB_TOP], 1u);
;             const unsigned tg = og / nx;
;             if (og + 1u == (tg + 1u) * nx) xb_add(&bar[XB_TOPGEN], 1u);
;             else XB_SPIN(xb_ld(&bar[XB_TOPGEN]) == tg, bar);
;             __builtin_amdgcn_fence(__ATOMIC_ACQUIRE, "agent");
;             xb_add(&bar[XB_XGEN(b.x)], 1u);
;             asm volatile("s_waitcnt vmcnt(0)" ::: "memory");
.LBB0_96:
	s_or_b64 exec, exec, s[8:9]
	s_mov_b64 s[8:9], exec
	v_mbcnt_lo_u32_b32 v0, s8, 0
	v_mbcnt_hi_u32_b32 v0, s9, v0
	v_cmp_eq_u32_e32 vcc, 0, v0
	s_nop 0
	buffer_inv sc1
	s_waitcnt vmcnt(0)
	s_and_saveexec_b64 s[18:19], vcc
	s_cbranch_execz .LBB0_98
	s_bcnt1_i32_b64 s8, s[8:9]
	v_mov_b32_e32 v0, 0x2000
	v_mov_b32_e32 v1, s8
	global_atomic_add v0, v1, s[6:7] offset:1024
.LBB0_98:
	s_or_b64 exec, exec, s[18:19]
	s_nop 0

; __device__ __forceinline__ unsigned xb_ld(unsigned* p)              { return __hip_atomic_load(p, __ATOMIC_RELAXED, __HIP_MEMORY_SCOPE_AGENT); }
; __device__ __forceinline__ unsigned xb_add(unsigned* p, unsigned v) { return __hip_atomic_fetch_add(p, v, __ATOMIC_RELAXED, __HIP_MEMORY_SCOPE_AGENT); }
; #define XB_SPIN(cond, bar) do { unsigned _sp = 0; while (cond) { __builtin_amdgcn_s_sleep(1); \
;     if ((++_sp & 255u) == 0u) { if (xb_ld(&(bar)[XB_TMO])) break; if (_sp > XB_SPIN_CAP) { atomicAdd(&(bar)[XB_TMO], 1u); break; } } } } while (0)
; __device__ __forceinline__ void xcd_barrier(const XcdBarrier& b, int wave_id) {
;     ...
;             const unsigned og = xb_add(&bar[XB_TOP], 1u);
;             const unsigned tg = og / nx;
;             if (og + 1u == (tg + 1u) * nx) xb_add(&bar[XB_TOPGEN], 1u);
;             else XB_SPIN(xb_ld(&bar[XB_TOPGEN]) == tg, bar);
;             __builtin_amdgcn_fence(__ATOMIC_ACQUIRE, "agent");
;             xb_add(&bar[XB_XGEN(b.x)], 1u);
;             asm volatile("s_waitcnt vmcnt(0)" ::: "memory");
.LBB0_256:
	s_or_b64 exec, exec, s[8:9]
	s_mov_b64 s[8:9], exec
	v_mbcnt_lo_u32_b32 v0, s8, 0
	v_mbcnt_hi_u32_b32 v0, s9, v0
	v_cmp_eq_u32_e32 vcc, 0, v0
	s_nop 0
	buffer_inv sc1
	s_waitcnt vmcnt(0)
	s_and_saveexec_b64 s[10:11], vcc
	s_cbranch_execz .LBB0_258
	s_bcnt1_i32_b64 s8, s[8:9]
	v_mov_b32_e32 v0, 0x2000
	v_mov_b32_e32 v1, s8
	global_atomic_add v0, v1, s[6:7] offset:1024
.LBB0_258:
	s_or_b64 exec, exec, s[10:11]
	s_nop 0

; __device__ __forceinline__ unsigned xb_ld(unsigned* p)              { return __hip_atomic_load(p, __ATOMIC_RELAXED, __HIP_MEMORY_SCOPE_AGENT); }
; __device__ __forceinline__ unsigned xb_add(unsigned* p, unsigned v) { return __hip_atomic_fetch_add(p, v, __ATOMIC_RELAXED, __HIP_MEMORY_SCOPE_AGENT); }
; #define XB_SPIN(cond, bar) do { unsigned _sp = 0; while (cond) { __builtin_amdgcn_s_sleep(1); \
;     if ((++_sp & 255u) == 0u) { if (xb_ld(&(bar)[XB_TMO])) break; if (_sp > XB_SPIN_CAP) { atomicAdd(&(bar)[XB_TMO], 1u); break; } } } } while (0)
; __device__ __forceinline__ void xcd_barrier(const XcdBarrier& b, int wave_id) {
;     ...
;             const unsigned og = xb_add(&bar[XB_TOP], 1u);
;             const unsigned tg = og / nx;
;             if (og + 1u == (tg + 1u) * nx) xb_add(&bar[XB_TOPGEN], 1u);
;             else XB_SPIN(xb_ld(&bar[XB_TOPGEN]) == tg, bar);
;             __builtin_amdgcn_fence(__ATOMIC_ACQUIRE, "agent");
;             xb_add(&bar[XB_XGEN(b.x)], 1u);
;             asm volatile("s_waitcnt vmcnt(0)" ::: "memory");
.LBB0_418:
	s_or_b64 exec, exec, s[20:21]
	s_mov_b64 s[20:21], exec
	v_mbcnt_lo_u32_b32 v0, s20, 0
	v_mbcnt_hi_u32_b32 v0, s21, v0
	v_cmp_eq_u32_e32 vcc, 0, v0
	s_nop 0
	buffer_inv sc1
	s_waitcnt vmcnt(0)
	s_and_saveexec_b64 s[22:23], vcc
	s_cbranch_execz .LBB0_420
	s_bcnt1_i32_b64 s6, s[20:21]
	v_mov_b32_e32 v0, 0x2000
	v_mov_b32_e32 v1, s6
	global_atomic_add v0, v1, s[10:11] offset:1024
.LBB0_420:
	s_or_b64 exec, exec, s[22:23]
	s_nop 0

; __device__ __forceinline__ unsigned xb_ld(unsigned* p)              { return __hip_atomic_load(p, __ATOMIC_RELAXED, __HIP_MEMORY_SCOPE_AGENT); }
; __device__ __forceinline__ unsigned xb_add(unsigned* p, unsigned v) { return __hip_atomic_fetch_add(p, v, __ATOMIC_RELAXED, __HIP_MEMORY_SCOPE_AGENT); }
; #define XB_SPIN(cond, bar) do { unsigned _sp = 0; while (cond) { __builtin_amdgcn_s_sleep(1); \
;     if ((++_sp & 255u) == 0u) { if (xb_ld(&(bar)[XB_TMO])) break; if (_sp > XB_SPIN_CAP) { atomicAdd(&(bar)[XB_TMO], 1u); break; } } } } while (0)
; __device__ __forceinline__ void xcd_barrier(const XcdBarrier& b, int wave_id) {
;     ...
;             const unsigned og = xb_add(&bar[XB_TOP], 1u);
;             const unsigned tg = og / nx;
;             if (og + 1u == (tg + 1u) * nx) xb_add(&bar[XB_TOPGEN], 1u);
;             else XB_SPIN(xb_ld(&bar[XB_TOPGEN]) == tg, bar);
;             __builtin_amdgcn_fence(__ATOMIC_ACQUIRE, "agent");
;             xb_add(&bar[XB_XGEN(b.x)], 1u);
;             asm volatile("s_waitcnt vmcnt(0)" ::: "memory");
.LBB0_501:
	s_or_b64 exec, exec, s[10:11]
	s_mov_b64 s[10:11], exec
	v_mbcnt_lo_u32_b32 v0, s10, 0
	v_mbcnt_hi_u32_b32 v0, s11, v0
	v_cmp_eq_u32_e32 vcc, 0, v0
	s_nop 0
	buffer_inv sc1
	s_waitcnt vmcnt(0)
	s_and_saveexec_b64 s[22:23], vcc
	s_cbranch_execz .LBB0_503
	s_bcnt1_i32_b64 s6, s[10:11]
	v_mov_b32_e32 v0, 0x2000
	v_mov_b32_e32 v1, s6
	global_atomic_add v0, v1, s[8:9] offset:1024

; __device__ __forceinline__ unsigned xb_ld(unsigned* p)              { return __hip_atomic_load(p, __ATOMIC_RELAXED, __HIP_MEMORY_SCOPE_AGENT); }
; __device__ __forceinline__ unsigned xb_add(unsigned* p, unsigned v) { return __hip_atomic_fetch_add(p, v, __ATOMIC_RELAXED, __HIP_MEMORY_SCOPE_AGENT); }
; #define XB_SPIN(cond, bar) do { unsigned _sp = 0; while (cond) { __builtin_amdgcn_s_sleep(1); \
;     if ((++_sp & 255u) == 0u) { if (xb_ld(&(bar)[XB_TMO])) break; if (_sp > XB_SPIN_CAP) { atomicAdd(&(bar)[XB_TMO], 1u); break; } } } } while (0)
; __device__ __forceinline__ void xcd_barrier(const XcdBarrier& b, int wave_id) {
;     ...
;             const unsigned og = xb_add(&bar[XB_TOP], 1u);
;             const unsigned tg = og / nx;
;             if (og + 1u == (tg + 1u) * nx) xb_add(&bar[XB_TOPGEN], 1u);
;             else XB_SPIN(xb_ld(&bar[XB_TOPGEN]) == tg, bar);
;             __builtin_amdgcn_fence(__ATOMIC_ACQUIRE, "agent");
;             xb_add(&bar[XB_XGEN(b.x)], 1u);
;             asm volatile("s_waitcnt vmcnt(0)" ::: "memory");
.LBB0_609:
	s_or_b64 exec, exec, s[8:9]
	s_mov_b64 s[8:9], exec
	v_mbcnt_lo_u32_b32 v0, s8, 0
	v_mbcnt_hi_u32_b32 v0, s9, v0
	v_cmp_eq_u32_e32 vcc, 0, v0
	s_nop 0
	buffer_inv sc1
	s_waitcnt vmcnt(0)
	s_and_saveexec_b64 s[22:23], vcc
	s_cbranch_execz .LBB0_611
	s_bcnt1_i32_b64 s8, s[8:9]
	v_mov_b32_e32 v0, 0x2000
	v_mov_b32_e32 v1, s8
	global_atomic_add v0, v1, s[6:7] offset:1024

; __device__ __forceinline__ unsigned xb_ld(unsigned* p)              { return __hip_atomic_load(p, __ATOMIC_RELAXED, __HIP_MEMORY_SCOPE_AGENT); }
; __device__ __forceinline__ unsigned xb_add(unsigned* p, unsigned v) { return __hip_atomic_fetch_add(p, v, __ATOMIC_RELAXED, __HIP_MEMORY_SCOPE_AGENT); }
; #define XB_SPIN(cond, bar) do { unsigned _sp = 0; while (cond) { __builtin_amdgcn_s_sleep(1); \
;     if ((++_sp & 255u) == 0u) { if (xb_ld(&(bar)[XB_TMO])) break; if (_sp > XB_SPIN_CAP) { atomicAdd(&(bar)[XB_TMO], 1u); break; } } } } while (0)
; __device__ __forceinline__ void xcd_barrier(const XcdBarrier& b, int wave_id) {
;     ...
;             const unsigned og = xb_add(&bar[XB_TOP], 1u);
;             const unsigned tg = og / nx;
;             if (og + 1u == (tg + 1u) * nx) xb_add(&bar[XB_TOPGEN], 1u);
;             else XB_SPIN(xb_ld(&bar[XB_TOPGEN]) == tg, bar);
;             __builtin_amdgcn_fence(__ATOMIC_ACQUIRE, "agent");
;             xb_add(&bar[XB_XGEN(b.x)], 1u);
;             asm volatile("s_waitcnt vmcnt(0)" ::: "memory");
.LBB0_705:
	s_or_b64 exec, exec, s[8:9]
	s_mov_b64 s[8:9], exec
	v_mbcnt_lo_u32_b32 v0, s8, 0
	v_mbcnt_hi_u32_b32 v0, s9, v0
	v_cmp_eq_u32_e32 vcc, 0, v0
	s_nop 0
	buffer_inv sc1
	s_waitcnt vmcnt(0)
	s_and_saveexec_b64 s[16:17], vcc
	s_cbranch_execz .LBB0_707
	s_bcnt1_i32_b64 s8, s[8:9]
	v_mov_b32_e32 v0, 0x2000
	v_mov_b32_e32 v1, s8
	global_atomic_add v0, v1, s[6:7] offset:1024
.LBB0_707:
	s_or_b64 exec, exec, s[16:17]
	s_nop 0

; __device__ __forceinline__ unsigned xb_ld(unsigned* p)              { return __hip_atomic_load(p, __ATOMIC_RELAXED, __HIP_MEMORY_SCOPE_AGENT); }
; __device__ __forceinline__ unsigned xb_add(unsigned* p, unsigned v) { return __hip_atomic_fetch_add(p, v, __ATOMIC_RELAXED, __HIP_MEMORY_SCOPE_AGENT); }
; #define XB_SPIN(cond, bar) do { unsigned _sp = 0; while (cond) { __builtin_amdgcn_s_sleep(1); \
;     if ((++_sp & 255u) == 0u) { if (xb_ld(&(bar)[XB_TMO])) break; if (_sp > XB_SPIN_CAP) { atomicAdd(&(bar)[XB_TMO], 1u); break; } } } } while (0)
; __device__ __forceinline__ void xcd_barrier(const XcdBarrier& b, int wave_id) {
;     ...
;             const unsigned og = xb_add(&bar[XB_TOP], 1u);
;             const unsigned tg = og / nx;
;             if (og + 1u == (tg + 1u) * nx) xb_add(&bar[XB_TOPGEN], 1u);
;             else XB_SPIN(xb_ld(&bar[XB_TOPGEN]) == tg, bar);
;             __builtin_amdgcn_fence(__ATOMIC_ACQUIRE, "agent");
;             xb_add(&bar[XB_XGEN(b.x)], 1u);
;             asm volatile("s_waitcnt vmcnt(0)" ::: "memory");
.LBB0_781:
	s_or_b64 exec, exec, s[14:15]
	s_mov_b64 s[14:15], exec
	v_mbcnt_lo_u32_b32 v0, s14, 0
	v_mbcnt_hi_u32_b32 v0, s15, v0
	v_cmp_eq_u32_e32 vcc, 0, v0
	s_nop 0
	buffer_inv sc1
	s_waitcnt vmcnt(0)
	s_and_saveexec_b64 s[16:17], vcc
	s_cbranch_execz .LBB0_783
	s_bcnt1_i32_b64 s3, s[14:15]
	v_mov_b32_e32 v0, 0x2000
	v_mov_b32_e32 v1, s3
	global_atomic_add v0, v1, s[4:5] offset:1024
